# attention steady loop: constant-0 rescale flag test, taken branch and unreachable rescale block removed (loop-edge cleanup)
# speedup vs baseline: 1.0040x; 1.0040x over previous
.LBB0_1045:
	s_waitcnt lgkmcnt(14)
	v_mfma_f32_32x32x16_bf16 v[32:47], v[140:143], v[176:179], v[32:47]
	v_exp_f32_e32 v96, v96
	v_exp_f32_e32 v97, v97
	v_exp_f32_e32 v98, v98
	v_exp_f32_e32 v99, v99
	s_waitcnt lgkmcnt(12)
	v_mfma_f32_32x32x16_bf16 v[16:31], v[140:143], v[172:175], v[16:31]
	v_exp_f32_e32 v100, v100
	v_exp_f32_e32 v101, v101
	v_exp_f32_e32 v102, v102
	v_exp_f32_e32 v103, v103
	v_add_u32_e32 v0, s57, v218
	ds_read_b128 v[160:163], v0
	ds_read_b128 v[152:155], v0 offset:512
	s_waitcnt lgkmcnt(12)
	v_mfma_f32_32x32x16_bf16 v[32:47], v[136:139], v[10:13], v[32:47]
	v_exp_f32_e32 v104, v104
	v_exp_f32_e32 v105, v105
	v_exp_f32_e32 v106, v106
	v_exp_f32_e32 v107, v107
	ds_read_b128 v[156:159], v0 offset:2048
	ds_read_b128 v[144:147], v0 offset:2560
	s_waitcnt lgkmcnt(12)
	v_mfma_f32_32x32x16_bf16 v[16:31], v[136:139], v[6:9], v[16:31]
	v_exp_f32_e32 v108, v108
	v_exp_f32_e32 v109, v109
	v_exp_f32_e32 v110, v110
	v_exp_f32_e32 v111, v111
	ds_read_b128 v[148:151], v0 offset:4096
	ds_read_b128 v[6:9], v0 offset:4608
	s_waitcnt lgkmcnt(12)
	v_mfma_f32_32x32x16_bf16 v[32:47], v[132:135], v[2:5], v[32:47]
	v_exp_f32_e32 v80, v80
	v_exp_f32_e32 v81, v81
	v_exp_f32_e32 v82, v82
	v_exp_f32_e32 v83, v83
	ds_read_b128 v[10:13], v0 offset:6144
	ds_read_b128 v[2:5], v0 offset:6656
	s_waitcnt lgkmcnt(12)
	v_mfma_f32_32x32x16_bf16 v[16:31], v[132:135], v[64:67], v[16:31]
	v_exp_f32_e32 v84, v84
	v_exp_f32_e32 v85, v85
	v_exp_f32_e32 v86, v86
	v_exp_f32_e32 v87, v87
	s_waitcnt lgkmcnt(10)
	v_mfma_f32_32x32x16_bf16 v[32:47], v[124:127], v[52:55], v[32:47]
	v_exp_f32_e32 v88, v88
	v_exp_f32_e32 v89, v89
	v_exp_f32_e32 v90, v90
	v_exp_f32_e32 v91, v91
	s_waitcnt lgkmcnt(8)
	v_mfma_f32_32x32x16_bf16 v[16:31], v[124:127], v[48:51], v[16:31]
	v_exp_f32_e32 v92, v92
	v_exp_f32_e32 v93, v93
	v_exp_f32_e32 v94, v94
	v_exp_f32_e32 v95, v95
	s_waitcnt vmcnt(2) lgkmcnt(0)
	s_barrier
	v_add_u32_e32 v0, s85, v217
.LBB0_1047:
	s_add_i32 s52, s57, 0x2000
	ds_read_b128 v[48:51], v185 offset:256
	ds_read_b128 v[52:55], v185 offset:288
	ds_read_b128 v[56:59], v185 offset:320
	ds_read_b128 v[60:63], v185 offset:352
	ds_read_b128 v[164:167], v185 offset:384
	ds_read_b128 v[168:171], v185 offset:416
	ds_read_b128 v[172:175], v185 offset:448
	ds_read_b128 v[176:179], v185 offset:480
	s_cmpk_lg_i32 s57, 0x4000
	s_waitcnt lgkmcnt(4)
	v_sub_f32_e32 v79, v63, v220
	v_sub_f32_e32 v78, v62, v220
	v_sub_f32_e32 v77, v61, v220
	v_sub_f32_e32 v76, v60, v220
	v_sub_f32_e32 v75, v59, v220
	v_sub_f32_e32 v74, v58, v220
	v_sub_f32_e32 v73, v57, v220
	v_sub_f32_e32 v72, v56, v220
	v_sub_f32_e32 v71, v55, v220
	v_sub_f32_e32 v70, v54, v220
	v_sub_f32_e32 v69, v53, v220
	v_sub_f32_e32 v68, v52, v220
	v_sub_f32_e32 v67, v51, v220
	v_sub_f32_e32 v66, v50, v220
	v_sub_f32_e32 v65, v49, v220
	v_sub_f32_e32 v64, v48, v220
	s_waitcnt lgkmcnt(0)
	v_sub_f32_e32 v63, v179, v220
	v_sub_f32_e32 v62, v178, v220
	v_sub_f32_e32 v61, v177, v220
	v_sub_f32_e32 v60, v176, v220
	v_sub_f32_e32 v59, v175, v220
	v_sub_f32_e32 v58, v174, v220
	v_sub_f32_e32 v57, v173, v220
	v_sub_f32_e32 v56, v172, v220
	v_sub_f32_e32 v55, v171, v220
	v_sub_f32_e32 v54, v170, v220
	v_sub_f32_e32 v53, v169, v220
	v_sub_f32_e32 v52, v168, v220
	v_sub_f32_e32 v51, v167, v220
	v_sub_f32_e32 v50, v166, v220
	v_sub_f32_e32 v49, v165, v220
	v_sub_f32_e32 v48, v164, v220
	s_cselect_b32 s89, s52, 0
	v_add_u32_e32 v15, s59, v219
	ds_read_b64_tr_b16 v[164:165], v15 offset:24576
	ds_read_b64_tr_b16 v[166:167], v15 offset:25088
	v_mfma_f32_32x32x16_bf16 v[64:79], v[160:163], v[128:131], v[64:79]
	v_add_f32_e32 v124, v96, v97
	v_add_f32_e32 v124, v98, v124
	v_add_f32_e32 v124, v99, v124
	v_add_f32_e32 v124, v100, v124
	v_add_f32_e32 v124, v101, v124
	v_cvt_pk_bf16_f32 v140, v96, v97
	v_cvt_pk_bf16_f32 v141, v98, v99
	ds_read_b64_tr_b16 v[160:161], v15 offset:28672
	ds_read_b64_tr_b16 v[162:163], v15 offset:29184
	v_mfma_f32_32x32x16_bf16 v[48:63], v[152:155], v[128:131], v[48:63]
	v_add_f32_e32 v96, v102, v124
	v_add_f32_e32 v96, v103, v96
	v_add_f32_e32 v96, v104, v96
	v_add_f32_e32 v96, v105, v96
	v_cvt_pk_bf16_f32 v142, v100, v101
	v_cvt_pk_bf16_f32 v143, v102, v103
	ds_read_b64_tr_b16 v[152:153], v15 offset:25600
	ds_read_b64_tr_b16 v[154:155], v15 offset:26112
	v_mfma_f32_32x32x16_bf16 v[64:79], v[156:159], v[120:123], v[64:79]
	v_add_f32_e32 v96, v106, v96
	v_add_f32_e32 v96, v107, v96
	v_add_f32_e32 v96, v108, v96
	v_add_f32_e32 v96, v109, v96
	v_cvt_pk_bf16_f32 v136, v104, v105
	v_cvt_pk_bf16_f32 v137, v106, v107
	ds_read_b64_tr_b16 v[104:105], v15 offset:29696
	ds_read_b64_tr_b16 v[106:107], v15 offset:30208
	v_mfma_f32_32x32x16_bf16 v[48:63], v[144:147], v[120:123], v[48:63]
	v_add_f32_e32 v96, v110, v96
	v_add_f32_e32 v96, v111, v96
	v_add_f32_e32 v96, v80, v96
	v_add_f32_e32 v96, v81, v96
	v_cvt_pk_bf16_f32 v138, v108, v109
	v_cvt_pk_bf16_f32 v139, v110, v111
	ds_read_b64_tr_b16 v[100:101], v15 offset:26624
	ds_read_b64_tr_b16 v[102:103], v15 offset:27136
	v_mfma_f32_32x32x16_bf16 v[64:79], v[148:151], v[116:119], v[64:79]
	v_add_f32_e32 v96, v82, v96
	v_add_f32_e32 v96, v83, v96
	v_add_f32_e32 v96, v84, v96
	v_add_f32_e32 v108, v85, v96
	v_cvt_pk_bf16_f32 v132, v80, v81
	v_cvt_pk_bf16_f32 v133, v82, v83
	ds_read_b64_tr_b16 v[96:97], v15 offset:30720
	ds_read_b64_tr_b16 v[98:99], v15 offset:31232
	v_mfma_f32_32x32x16_bf16 v[48:63], v[6:9], v[116:119], v[48:63]
	v_add_f32_e32 v80, v86, v108
	v_add_f32_e32 v80, v87, v80
	v_add_f32_e32 v80, v88, v80
	v_add_f32_e32 v108, v89, v80
	v_cvt_pk_bf16_f32 v134, v84, v85
	v_cvt_pk_bf16_f32 v135, v86, v87
	ds_read_b64_tr_b16 v[80:81], v15 offset:27648
	ds_read_b64_tr_b16 v[82:83], v15 offset:28160
	v_mfma_f32_32x32x16_bf16 v[64:79], v[10:13], v[112:115], v[64:79]
	v_add_f32_e32 v6, v90, v108
	v_add_f32_e32 v6, v91, v6
	v_add_f32_e32 v6, v92, v6
	v_add_f32_e32 v84, v93, v6
	v_cvt_pk_bf16_f32 v124, v88, v89
	v_cvt_pk_bf16_f32 v125, v90, v91
	ds_read_b64_tr_b16 v[6:7], v15 offset:31744
	ds_read_b64_tr_b16 v[8:9], v15 offset:32256
	v_mfma_f32_32x32x16_bf16 v[48:63], v[2:5], v[112:115], v[48:63]
	v_add_f32_e32 v10, v94, v84
	v_add_f32_e32 v10, v95, v10
	v_add_f32_e32 v10, 0, v10
	v_cvt_pk_bf16_f32 v126, v92, v93
	v_cvt_pk_bf16_f32 v127, v94, v95
	s_nop 3
	s_add_i32 s52, s57, s86
	s_mov_b32 s53, m0
	s_mov_b32 m0, s52
	s_nop 0
	global_load_lds_dwordx4 v[182:183], off
	s_mov_b32 m0, s53
	s_add_i32 s52, s89, s87
	s_mov_b32 s53, m0
	s_mov_b32 m0, s52
	s_nop 0
	global_load_lds_dwordx4 v[180:181], off
	s_mov_b32 m0, s53
	v_add_f32_e32 v221, v14, v10
.LBB0_1048:
	s_waitcnt lgkmcnt(14)
	v_mfma_f32_32x32x16_bf16 v[32:47], v[140:143], v[164:167], v[32:47]
	v_exp_f32_e32 v64, v64
	v_exp_f32_e32 v65, v65
	v_exp_f32_e32 v66, v66
	v_exp_f32_e32 v67, v67
	s_waitcnt lgkmcnt(12)
	v_mfma_f32_32x32x16_bf16 v[16:31], v[140:143], v[160:163], v[16:31]
	v_exp_f32_e32 v68, v68
	v_exp_f32_e32 v69, v69
	v_exp_f32_e32 v70, v70
	v_exp_f32_e32 v71, v71
	v_add_u32_e32 v2, s89, v218
	ds_read_b128 v[172:175], v2
	ds_read_b128 v[168:171], v2 offset:512
	s_waitcnt lgkmcnt(12)
	v_mfma_f32_32x32x16_bf16 v[32:47], v[136:139], v[152:155], v[32:47]
	v_exp_f32_e32 v72, v72
	v_exp_f32_e32 v73, v73
	v_exp_f32_e32 v74, v74
	v_exp_f32_e32 v75, v75
	ds_read_b128 v[164:167], v2 offset:2048
	ds_read_b128 v[160:163], v2 offset:2560
	s_waitcnt lgkmcnt(12)
	v_mfma_f32_32x32x16_bf16 v[16:31], v[136:139], v[104:107], v[16:31]
	v_exp_f32_e32 v76, v76
	v_exp_f32_e32 v77, v77
	v_exp_f32_e32 v78, v78
	v_exp_f32_e32 v79, v79
	ds_read_b128 v[156:159], v2 offset:4096
	ds_read_b128 v[152:155], v2 offset:4608
	s_waitcnt lgkmcnt(12)
	v_mfma_f32_32x32x16_bf16 v[32:47], v[132:135], v[100:103], v[32:47]
	v_exp_f32_e32 v48, v48
	v_exp_f32_e32 v49, v49
	v_exp_f32_e32 v50, v50
	v_exp_f32_e32 v51, v51
	ds_read_b128 v[148:151], v2 offset:6144
	ds_read_b128 v[144:147], v2 offset:6656
	s_waitcnt lgkmcnt(12)
	v_mfma_f32_32x32x16_bf16 v[16:31], v[132:135], v[96:99], v[16:31]
	v_exp_f32_e32 v52, v52
	v_exp_f32_e32 v53, v53
	v_exp_f32_e32 v54, v54
	v_exp_f32_e32 v55, v55
	s_waitcnt lgkmcnt(10)
	v_mfma_f32_32x32x16_bf16 v[32:47], v[124:127], v[80:83], v[32:47]
	v_exp_f32_e32 v56, v56
	v_exp_f32_e32 v57, v57
	v_exp_f32_e32 v58, v58
	v_exp_f32_e32 v59, v59
	s_waitcnt lgkmcnt(8)
	v_mfma_f32_32x32x16_bf16 v[16:31], v[124:127], v[6:9], v[16:31]
	v_exp_f32_e32 v60, v60
	v_exp_f32_e32 v61, v61
	v_exp_f32_e32 v62, v62
	v_exp_f32_e32 v63, v63
	s_waitcnt vmcnt(2) lgkmcnt(0)
	s_barrier
.LBB0_1050:
	s_add_i32 s52, s89, 0x2000
	s_cmpk_lg_i32 s89, 0x4000
	s_cselect_b32 s90, s52, 0
	s_add_i32 s52, s58, 2
	v_lshl_add_u64 v[180:181], v[180:181], 0, s[18:19]
	v_lshl_add_u64 v[182:183], v[182:183], 0, s[18:19]
	s_cmp_ge_i32 s52, s88
	v_add_u32_e32 v185, 0x200, v185
	s_cbranch_scc1 .LBB0_1077
	s_mov_b32 s58, s52
	s_mov_b32 s52, s57
	s_mov_b32 s59, s89
	s_mov_b32 s57, s90
	s_branch .LBB0_1044
